# P7 split-K fix-up: all 34 loads in one batch (27 + 5 partial + 2 residual rows), stacked on v85
# baseline (speedup 1.0000x reference)
.LBB0_1484:
	s_or_b64 exec, exec, s[50:51]
	s_lshr_b32 s33, s53, 2
	s_and_b32 s73, s53, 3
	v_mov_b32_e32 v130, v0
	s_lshl_b32 s7, s33, 4
	s_lshl_b32 s11, s73, 1
	s_barrier
	s_or_b32 s18, s7, s11
	v_ashrrev_i32_e32 v131, 31, v130
	s_ashr_i32 s7, s6, 31
	v_lshl_add_u64 v[130:131], v[130:131], 4, s[68:69]
	s_or_b32 s44, s18, 8
	s_lshl_b64 s[20:21], s[6:7], 17
	s_mov_b32 s19, s45
	s_lshl_b64 s[50:51], s[44:45], 12
	v_lshl_add_u64 v[132:133], v[130:131], 0, s[20:21]
	s_lshl_b64 s[86:87], s[18:19], 12
	s_or_b32 s44, s18, 1
	v_lshl_add_u64 v[134:135], v[132:133], 0, s[86:87]
	s_add_u32 s88, s86, 8
	s_addc_u32 s89, s87, 0
	s_or_b32 s44, s18, 9
	s_or_b32 s18, s6, 1
	global_load_dwordx2 v[154:155], v[134:135], off sc1
	v_lshl_add_u64 v[134:135], v[132:133], 0, s[88:89]
	s_add_u32 s90, s50, 8
	s_addc_u32 s91, s51, 0
	s_ashr_i32 s19, s18, 31
	global_load_dwordx2 v[156:157], v[134:135], off sc1
	v_lshl_add_u64 v[134:135], v[132:133], 0, s[50:51]
	v_lshl_add_u64 v[132:133], v[132:133], 0, s[90:91]
	s_lshl_b64 s[18:19], s[18:19], 17
	global_load_dwordx2 v[158:159], v[134:135], off sc1
	global_load_dwordx2 v[160:161], v[132:133], off sc1
	v_lshl_add_u64 v[132:133], v[130:131], 0, s[18:19]
	v_lshl_add_u64 v[134:135], v[132:133], 0, s[86:87]
	s_or_b32 s18, s6, 2
	global_load_dwordx2 v[162:163], v[134:135], off sc1
	v_lshl_add_u64 v[134:135], v[132:133], 0, s[88:89]
	s_ashr_i32 s19, s18, 31
	global_load_dwordx2 v[164:165], v[134:135], off sc1
	v_lshl_add_u64 v[134:135], v[132:133], 0, s[50:51]
	v_lshl_add_u64 v[132:133], v[132:133], 0, s[90:91]
	s_lshl_b64 s[18:19], s[18:19], 17
	global_load_dwordx2 v[166:167], v[134:135], off sc1
	global_load_dwordx2 v[168:169], v[132:133], off sc1
	v_lshl_add_u64 v[132:133], v[130:131], 0, s[18:19]
	v_lshl_add_u64 v[134:135], v[132:133], 0, s[86:87]
	s_or_b32 s18, s6, 3
	global_load_dwordx2 v[170:171], v[134:135], off sc1
	v_lshl_add_u64 v[134:135], v[132:133], 0, s[88:89]
	s_ashr_i32 s19, s18, 31
	global_load_dwordx2 v[172:173], v[134:135], off sc1
	v_lshl_add_u64 v[134:135], v[132:133], 0, s[50:51]
	v_lshl_add_u64 v[132:133], v[132:133], 0, s[90:91]
	s_lshl_b64 s[18:19], s[18:19], 17
	global_load_dwordx2 v[174:175], v[134:135], off sc1
	global_load_dwordx2 v[176:177], v[132:133], off sc1
	v_lshl_add_u64 v[132:133], v[130:131], 0, s[18:19]
	v_lshl_add_u64 v[134:135], v[132:133], 0, s[86:87]
	s_or_b32 s18, s6, 4
	global_load_dwordx2 v[178:179], v[134:135], off sc1
	v_lshl_add_u64 v[134:135], v[132:133], 0, s[88:89]
	s_ashr_i32 s19, s18, 31
	global_load_dwordx2 v[180:181], v[134:135], off sc1
	v_lshl_add_u64 v[134:135], v[132:133], 0, s[50:51]
	v_lshl_add_u64 v[132:133], v[132:133], 0, s[90:91]
	s_lshl_b64 s[18:19], s[18:19], 17
	global_load_dwordx2 v[182:183], v[134:135], off sc1
	global_load_dwordx2 v[184:185], v[132:133], off sc1
	v_lshl_add_u64 v[132:133], v[130:131], 0, s[18:19]
	v_lshl_add_u64 v[134:135], v[132:133], 0, s[86:87]
	global_load_dwordx2 v[196:197], v[134:135], off sc1
	v_lshl_add_u64 v[134:135], v[132:133], 0, s[88:89]
	global_load_dwordx2 v[198:199], v[134:135], off sc1
	v_lshl_add_u64 v[134:135], v[132:133], 0, s[50:51]
	global_load_dwordx2 v[200:201], v[134:135], off sc1
	s_or_b32 s18, s6, 5
	s_ashr_i32 s19, s18, 31
	v_lshl_add_u64 v[132:133], v[132:133], 0, s[90:91]
	s_lshl_b64 s[18:19], s[18:19], 17
	global_load_dwordx2 v[202:203], v[132:133], off sc1
	v_lshl_add_u64 v[132:133], v[130:131], 0, s[18:19]
	v_lshl_add_u64 v[134:135], v[132:133], 0, s[86:87]
	global_load_dwordx2 v[152:153], v[134:135], off sc1
	v_lshl_add_u64 v[134:135], v[132:133], 0, s[88:89]
	global_load_dwordx2 v[150:151], v[134:135], off sc1
	v_lshl_add_u64 v[134:135], v[132:133], 0, s[50:51]
	global_load_dwordx2 v[148:149], v[134:135], off sc1
	v_lshl_add_u64 v[132:133], v[132:133], 0, s[90:91]
	global_load_dwordx2 v[144:145], v[132:133], off sc1
	s_or_b32 s18, s6, 6
	s_ashr_i32 s19, s18, 31
	s_lshl_b64 s[18:19], s[18:19], 17
	v_lshl_add_u64 v[132:133], v[130:131], 0, s[18:19]
	v_lshl_add_u64 v[134:135], v[132:133], 0, s[86:87]
	s_or_b32 s6, s6, 7
	global_load_dwordx2 v[146:147], v[134:135], off sc1
	v_lshl_add_u64 v[134:135], v[132:133], 0, s[88:89]
	s_ashr_i32 s7, s6, 31
	global_load_dwordx2 v[142:143], v[134:135], off sc1
	v_lshl_add_u64 v[134:135], v[132:133], 0, s[50:51]
	s_lshl_b64 s[6:7], s[6:7], 17
	global_load_dwordx2 v[140:141], v[134:135], off sc1
	v_lshl_add_u64 v[132:133], v[132:133], 0, s[90:91]
	v_lshl_add_u64 v[130:131], v[130:131], 0, s[6:7]
	global_load_dwordx2 v[2:3], v[132:133], off sc1
	v_lshl_add_u64 v[132:133], v[130:131], 0, s[86:87]
	global_load_dwordx2 v[4:5], v[132:133], off sc1
	v_lshl_add_u64 v[132:133], v[130:131], 0, s[88:89]
	global_load_dwordx2 v[6:7], v[132:133], off sc1
	v_lshl_add_u64 v[132:133], v[130:131], 0, s[50:51]
	global_load_dwordx2 v[8:9], v[132:133], off sc1
	v_lshl_add_u64 v[130:131], v[130:131], 0, s[90:91]
	global_load_dwordx2 v[10:11], v[130:131], off sc1
	v_lshl_add_u32 v12, s33, 7, v214
	v_lshl_add_u32 v12, s24, 8, v12
	v_lshl_or_b32 v12, s73, 4, v12
	v_lshl_or_b32 v14, s10, 8, v217
	v_ashrrev_i32_e32 v13, 31, v12
	v_ashrrev_i32_e32 v15, 31, v14
	v_readlane_b32 s18, v254, 62
	v_readlane_b32 s19, v254, 63
	v_lshlrev_b64 v[12:13], 11, v[12:13]
	v_lshlrev_b64 v[14:15], 1, v[14:15]
	v_lshl_add_u64 v[12:13], s[18:19], 0, v[12:13]
	v_lshl_add_u64 v[12:13], v[12:13], 0, v[14:15]
	global_load_dwordx4 v[22:25], v[12:13], off
	global_load_dwordx4 v[26:29], v[12:13], off offset:256
	s_waitcnt vmcnt(33)
	v_lshlrev_b32_e32 v204, 16, v154
	v_and_b32_e32 v205, 0xffff0000, v154
	v_lshlrev_b32_e32 v154, 16, v155
	v_and_b32_e32 v155, 0xffff0000, v155
	v_pk_add_f32 v[154:155], v[154:155], 0 op_sel_hi:[1,0]
	s_waitcnt vmcnt(32)
	v_lshlrev_b32_e32 v206, 16, v156
	v_and_b32_e32 v207, 0xffff0000, v156
	v_lshlrev_b32_e32 v156, 16, v157
	v_and_b32_e32 v157, 0xffff0000, v157
	v_pk_add_f32 v[156:157], v[156:157], 0 op_sel_hi:[1,0]
	s_waitcnt vmcnt(31)
	v_lshlrev_b32_e32 v208, 16, v158
	v_and_b32_e32 v209, 0xffff0000, v158
	v_lshlrev_b32_e32 v158, 16, v159
	s_waitcnt vmcnt(29)
	v_lshlrev_b32_e32 v222, 16, v162
	v_and_b32_e32 v223, 0xffff0000, v162
	v_lshlrev_b32_e32 v162, 16, v163
	v_and_b32_e32 v163, 0xffff0000, v163
	v_and_b32_e32 v159, 0xffff0000, v159
	v_pk_add_f32 v[154:155], v[154:155], v[162:163]
	s_waitcnt vmcnt(28)
	v_lshlrev_b32_e32 v162, 16, v164
	v_and_b32_e32 v163, 0xffff0000, v164
	v_lshlrev_b32_e32 v164, 16, v165
	v_and_b32_e32 v165, 0xffff0000, v165
	v_pk_add_f32 v[158:159], v[158:159], 0 op_sel_hi:[1,0]
	v_lshlrev_b32_e32 v210, 16, v160
	v_and_b32_e32 v211, 0xffff0000, v160
	v_lshlrev_b32_e32 v160, 16, v161
	v_and_b32_e32 v161, 0xffff0000, v161
	v_pk_add_f32 v[156:157], v[156:157], v[164:165]
	s_waitcnt vmcnt(27)
	v_lshlrev_b32_e32 v164, 16, v166
	v_and_b32_e32 v165, 0xffff0000, v166
	v_lshlrev_b32_e32 v166, 16, v167
	v_and_b32_e32 v167, 0xffff0000, v167
	v_pk_add_f32 v[160:161], v[160:161], 0 op_sel_hi:[1,0]
	v_pk_add_f32 v[158:159], v[158:159], v[166:167]
	s_waitcnt vmcnt(26)
	v_lshlrev_b32_e32 v166, 16, v168
	v_and_b32_e32 v167, 0xffff0000, v168
	v_lshlrev_b32_e32 v168, 16, v169
	v_and_b32_e32 v169, 0xffff0000, v169
	v_pk_add_f32 v[160:161], v[160:161], v[168:169]
	s_waitcnt vmcnt(25)
	v_lshlrev_b32_e32 v168, 16, v170
	v_and_b32_e32 v169, 0xffff0000, v170
	v_lshlrev_b32_e32 v170, 16, v171
	v_and_b32_e32 v171, 0xffff0000, v171
	v_pk_add_f32 v[154:155], v[154:155], v[170:171]
	s_waitcnt vmcnt(24)
	v_lshlrev_b32_e32 v170, 16, v172
	v_and_b32_e32 v171, 0xffff0000, v172
	v_lshlrev_b32_e32 v172, 16, v173
	v_and_b32_e32 v173, 0xffff0000, v173
	v_pk_add_f32 v[206:207], v[206:207], 0 op_sel_hi:[1,0]
	v_pk_add_f32 v[156:157], v[156:157], v[172:173]
	s_waitcnt vmcnt(23)
	v_lshlrev_b32_e32 v172, 16, v175
	v_and_b32_e32 v173, 0xffff0000, v175
	v_pk_add_f32 v[208:209], v[208:209], 0 op_sel_hi:[1,0]
	v_pk_add_f32 v[162:163], v[206:207], v[162:163]
	v_pk_add_f32 v[158:159], v[158:159], v[172:173]
	s_waitcnt vmcnt(22)
	v_lshlrev_b32_e32 v172, 16, v177
	v_and_b32_e32 v173, 0xffff0000, v177
	v_pk_add_f32 v[204:205], v[204:205], 0 op_sel_hi:[1,0]
	v_pk_add_f32 v[210:211], v[210:211], 0 op_sel_hi:[1,0]
	v_pk_add_f32 v[164:165], v[208:209], v[164:165]
	v_pk_add_f32 v[162:163], v[162:163], v[170:171]
	v_lshlrev_b32_e32 v170, 16, v174
	v_and_b32_e32 v171, 0xffff0000, v174
	v_pk_add_f32 v[160:161], v[160:161], v[172:173]
	s_waitcnt vmcnt(21)
	v_lshlrev_b32_e32 v172, 16, v179
	v_and_b32_e32 v173, 0xffff0000, v179
	v_pk_add_f32 v[204:205], v[204:205], v[222:223]
	v_pk_add_f32 v[166:167], v[210:211], v[166:167]
	v_pk_add_f32 v[164:165], v[164:165], v[170:171]
	v_lshlrev_b32_e32 v170, 16, v176
	v_and_b32_e32 v171, 0xffff0000, v176
	v_pk_add_f32 v[154:155], v[154:155], v[172:173]
	s_waitcnt vmcnt(20)
	v_lshlrev_b32_e32 v172, 16, v181
	v_and_b32_e32 v173, 0xffff0000, v181
	v_pk_add_f32 v[168:169], v[204:205], v[168:169]
	v_pk_add_f32 v[166:167], v[166:167], v[170:171]
	v_lshlrev_b32_e32 v170, 16, v178
	v_and_b32_e32 v171, 0xffff0000, v178
	v_pk_add_f32 v[156:157], v[156:157], v[172:173]
	s_waitcnt vmcnt(19)
	v_lshlrev_b32_e32 v172, 16, v183
	v_and_b32_e32 v173, 0xffff0000, v183
	v_pk_add_f32 v[168:169], v[168:169], v[170:171]
	v_lshlrev_b32_e32 v170, 16, v180
	v_and_b32_e32 v171, 0xffff0000, v180
	v_pk_add_f32 v[158:159], v[158:159], v[172:173]
	s_waitcnt vmcnt(18)
	v_lshlrev_b32_e32 v172, 16, v185
	v_and_b32_e32 v173, 0xffff0000, v185
	v_pk_add_f32 v[162:163], v[162:163], v[170:171]
	v_lshlrev_b32_e32 v170, 16, v182
	v_and_b32_e32 v171, 0xffff0000, v182
	v_pk_add_f32 v[160:161], v[160:161], v[172:173]
	s_waitcnt vmcnt(17)
	v_lshlrev_b32_e32 v172, 16, v197
	v_and_b32_e32 v173, 0xffff0000, v197
	v_pk_add_f32 v[164:165], v[164:165], v[170:171]
	v_lshlrev_b32_e32 v170, 16, v184
	v_and_b32_e32 v171, 0xffff0000, v184
	v_pk_add_f32 v[172:173], v[154:155], v[172:173]
	s_waitcnt vmcnt(16)
	v_lshlrev_b32_e32 v154, 16, v198
	v_and_b32_e32 v155, 0xffff0000, v198
	v_pk_add_f32 v[166:167], v[166:167], v[170:171]
	v_lshlrev_b32_e32 v170, 16, v196
	v_and_b32_e32 v171, 0xffff0000, v196
	v_pk_add_f32 v[162:163], v[162:163], v[154:155]
	s_waitcnt vmcnt(15)
	v_lshlrev_b32_e32 v154, 16, v200
	v_and_b32_e32 v155, 0xffff0000, v200
	s_lshl_b32 s11, s24, 8
	v_lshl_add_u32 v182, s33, 7, v214
	v_pk_add_f32 v[168:169], v[168:169], v[170:171]
	v_lshlrev_b32_e32 v170, 16, v199
	v_and_b32_e32 v171, 0xffff0000, v199
	v_pk_add_f32 v[164:165], v[164:165], v[154:155]
	s_lshl_b32 s6, s73, 4
	v_add_u32_e32 v154, s11, v182
	v_pk_add_f32 v[170:171], v[156:157], v[170:171]
	v_lshlrev_b32_e32 v156, 16, v201
	v_and_b32_e32 v157, 0xffff0000, v201
	v_or_b32_e32 v154, s6, v154
	v_pk_add_f32 v[158:159], v[158:159], v[156:157]
	v_lshl_or_b32 v156, s10, 8, v217
	v_ashrrev_i32_e32 v155, 31, v154
	v_readlane_b32 s18, v254, 62
	v_ashrrev_i32_e32 v157, 31, v156
	v_lshlrev_b64 v[154:155], 11, v[154:155]
	v_readlane_b32 s19, v254, 63
	v_lshlrev_b64 v[178:179], 1, v[156:157]
	s_waitcnt vmcnt(14)
	v_lshlrev_b32_e32 v174, 16, v202
	v_lshl_add_u64 v[154:155], s[18:19], 0, v[154:155]
	v_lshl_add_u64 v[180:181], v[154:155], 0, v[178:179]
	v_and_b32_e32 v175, 0xffff0000, v202
	v_pk_add_f32 v[166:167], v[166:167], v[174:175]
	s_waitcnt vmcnt(13)
	v_lshlrev_b32_e32 v174, 16, v152
	v_and_b32_e32 v175, 0xffff0000, v152
	v_lshlrev_b32_e32 v152, 16, v153
	v_and_b32_e32 v153, 0xffff0000, v153
	v_pk_add_f32 v[152:153], v[172:173], v[152:153]
	s_waitcnt vmcnt(12)
	v_lshlrev_b32_e32 v172, 16, v150
	v_and_b32_e32 v173, 0xffff0000, v150
	v_lshlrev_b32_e32 v150, 16, v151
	v_and_b32_e32 v151, 0xffff0000, v151
	v_pk_add_f32 v[170:171], v[170:171], v[150:151]
	s_waitcnt vmcnt(11)
	v_lshlrev_b32_e32 v150, 16, v148
	v_and_b32_e32 v151, 0xffff0000, v148
	v_lshlrev_b32_e32 v148, 16, v149
	v_and_b32_e32 v149, 0xffff0000, v149
	v_pk_add_f32 v[158:159], v[158:159], v[148:149]
	s_waitcnt vmcnt(10)
	v_lshlrev_b32_e32 v148, 16, v144
	v_and_b32_e32 v149, 0xffff0000, v144
	v_pk_add_f32 v[164:165], v[164:165], v[150:151]
	v_pk_add_f32 v[166:167], v[166:167], v[148:149]
	v_lshlrev_b32_e32 v176, 16, v203
	v_and_b32_e32 v177, 0xffff0000, v203
	v_pk_add_f32 v[160:161], v[160:161], v[176:177]
	v_lshlrev_b32_e32 v144, 16, v145
	v_and_b32_e32 v145, 0xffff0000, v145
	v_pk_add_f32 v[168:169], v[168:169], v[174:175]
	v_pk_add_f32 v[144:145], v[160:161], v[144:145]
	s_waitcnt vmcnt(9)
	v_lshlrev_b32_e32 v160, 16, v146
	v_and_b32_e32 v161, 0xffff0000, v146
	v_lshlrev_b32_e32 v146, 16, v147
	v_and_b32_e32 v147, 0xffff0000, v147
	v_pk_add_f32 v[162:163], v[162:163], v[172:173]
	v_pk_add_f32 v[146:147], v[152:153], v[146:147]
	v_pk_add_f32 v[152:153], v[168:169], v[160:161]
	s_waitcnt vmcnt(8)
	v_lshlrev_b32_e32 v160, 16, v142
	v_and_b32_e32 v161, 0xffff0000, v142
	v_pk_add_f32 v[160:161], v[162:163], v[160:161]
	s_waitcnt vmcnt(7)
	v_lshlrev_b32_e32 v162, 16, v140
	v_and_b32_e32 v163, 0xffff0000, v140
	v_lshlrev_b32_e32 v140, 16, v141
	v_and_b32_e32 v141, 0xffff0000, v141
	v_pk_add_f32 v[140:141], v[158:159], v[140:141]
	v_pk_add_f32 v[158:159], v[164:165], v[162:163]
	s_waitcnt vmcnt(6)
	v_mov_b32_e32 v136, v2
	v_mov_b32_e32 v137, v3
	v_lshlrev_b32_e32 v162, 16, v136
	v_and_b32_e32 v163, 0xffff0000, v136
	v_lshlrev_b32_e32 v136, 16, v137
	v_and_b32_e32 v137, 0xffff0000, v137
	v_lshlrev_b32_e32 v142, 16, v143
	v_and_b32_e32 v143, 0xffff0000, v143
	v_pk_add_f32 v[136:137], v[144:145], v[136:137]
	v_pk_add_f32 v[144:145], v[166:167], v[162:163]
	s_waitcnt vmcnt(5)
	v_mov_b32_e32 v138, v4
	v_mov_b32_e32 v139, v5
	v_lshlrev_b32_e32 v162, 16, v138
	v_and_b32_e32 v163, 0xffff0000, v138
	v_lshlrev_b32_e32 v138, 16, v139
	v_and_b32_e32 v139, 0xffff0000, v139
	v_pk_add_f32 v[142:143], v[170:171], v[142:143]
	v_pk_add_f32 v[138:139], v[146:147], v[138:139]
	s_waitcnt vmcnt(4)
	v_mov_b32_e32 v134, v6
	v_mov_b32_e32 v135, v7
	v_lshlrev_b32_e32 v146, 16, v134
	v_and_b32_e32 v147, 0xffff0000, v134
	v_lshlrev_b32_e32 v134, 16, v135
	v_and_b32_e32 v135, 0xffff0000, v135
	v_pk_add_f32 v[134:135], v[142:143], v[134:135]
	s_waitcnt vmcnt(3)
	v_mov_b32_e32 v132, v8
	v_mov_b32_e32 v133, v9
	v_lshlrev_b32_e32 v142, 16, v132
	v_and_b32_e32 v143, 0xffff0000, v132
	v_lshlrev_b32_e32 v132, 16, v133
	v_and_b32_e32 v133, 0xffff0000, v133
	v_pk_add_f32 v[140:141], v[140:141], v[132:133]
	s_waitcnt vmcnt(2)
	v_mov_b32_e32 v130, v10
	v_mov_b32_e32 v131, v11
	v_lshlrev_b32_e32 v132, 16, v130
	v_and_b32_e32 v133, 0xffff0000, v130
	v_lshlrev_b32_e32 v130, 16, v131
	v_and_b32_e32 v131, 0xffff0000, v131
	v_pk_add_f32 v[136:137], v[136:137], v[130:131]
	v_or_b32_e32 v130, s6, v182
	v_pk_add_f32 v[144:145], v[144:145], v[132:133]
	v_add_u32_e32 v132, s11, v130
	v_ashrrev_i32_e32 v133, 31, v132
	v_pk_add_f32 v[152:153], v[152:153], v[162:163]
	v_pk_add_f32 v[142:143], v[158:159], v[142:143]
	v_lshlrev_b64 v[158:159], 11, v[132:133]
	s_waitcnt vmcnt(1)
	v_mov_b32_e32 v154, v22
	v_mov_b32_e32 v155, v23
	v_mov_b32_e32 v156, v24
	v_mov_b32_e32 v157, v25
	v_lshlrev_b32_e32 v132, 16, v154
	v_and_b32_e32 v133, 0xffff0000, v154
	v_lshlrev_b32_e32 v154, 16, v155
	v_and_b32_e32 v155, 0xffff0000, v155
	v_pk_add_f32 v[146:147], v[160:161], v[146:147]
	v_lshlrev_b32_e32 v160, 16, v156
	v_and_b32_e32 v161, 0xffff0000, v156
	v_lshlrev_b32_e32 v156, 16, v157
	v_and_b32_e32 v157, 0xffff0000, v157
	v_pk_add_f32 v[138:139], v[138:139], v[154:155]
	v_pk_add_f32 v[132:133], v[152:153], v[132:133]
	v_pk_add_f32 v[152:153], v[134:135], v[156:157]
	v_pk_add_f32 v[134:135], v[146:147], v[160:161]
	v_mul_f32_e32 v131, v133, v133
	v_mul_f32_e32 v146, v139, v139
	v_fmac_f32_e32 v131, v132, v132
	v_fmac_f32_e32 v146, v138, v138
	v_add_f32_e32 v131, v131, v146
	v_mul_f32_e32 v146, v135, v135
	v_mul_f32_e32 v147, v153, v153
	v_fmac_f32_e32 v146, v134, v134
	v_fmac_f32_e32 v147, v152, v152
	v_add_f32_e32 v146, v146, v147
	v_add_f32_e32 v131, v131, v146
	v_cvt_pk_bf16_f32 v132, v132, v133
	v_cvt_pk_bf16_f32 v133, v138, v139
	s_waitcnt vmcnt(0)
	v_mov_b32_e32 v148, v26
	v_mov_b32_e32 v149, v27
	v_mov_b32_e32 v150, v28
	v_mov_b32_e32 v151, v29
	v_lshlrev_b32_e32 v138, 16, v148
	v_and_b32_e32 v139, 0xffff0000, v148
	v_lshlrev_b32_e32 v146, 16, v149
	v_and_b32_e32 v147, 0xffff0000, v149
	v_lshlrev_b32_e32 v148, 16, v150
	v_and_b32_e32 v149, 0xffff0000, v150
	v_lshlrev_b32_e32 v150, 16, v151
	v_and_b32_e32 v151, 0xffff0000, v151
	v_pk_add_f32 v[140:141], v[140:141], v[146:147]
	v_pk_add_f32 v[138:139], v[142:143], v[138:139]
	v_pk_add_f32 v[142:143], v[136:137], v[150:151]
	v_pk_add_f32 v[136:137], v[144:145], v[148:149]
	v_mul_f32_e32 v144, v139, v139
	v_mul_f32_e32 v145, v141, v141
	v_fmac_f32_e32 v144, v138, v138
	v_fmac_f32_e32 v145, v140, v140
	v_add_f32_e32 v144, v144, v145
	v_mul_f32_e32 v145, v137, v137
	v_mul_f32_e32 v146, v143, v143
	v_fmac_f32_e32 v145, v136, v136
	v_fmac_f32_e32 v146, v142, v142
	v_add_f32_e32 v145, v145, v146
	v_add_f32_e32 v144, v144, v145
	v_and_b32_e32 v145, 64, v221
	v_add_f32_e32 v131, v131, v144
	v_xor_b32_e32 v144, 16, v221
	v_add_u32_e32 v146, 64, v145
	v_cmp_lt_i32_e32 vcc, v144, v146
	v_cvt_pk_bf16_f32 v134, v134, v135
	v_cvt_pk_bf16_f32 v135, v152, v153
	s_nop 1
	v_cndmask_b32_e32 v144, v221, v144, vcc
	v_lshlrev_b32_e32 v144, 2, v144
	v_mov_b32_e32 v147, v131
	s_nop 1
	v_permlane16_swap_b32_e32 v131, v147
	v_lshl_add_u64 v[144:145], s[42:43], 0, v[158:159]
	v_lshl_add_u64 v[144:145], v[144:145], 0, v[178:179]
	global_store_dwordx4 v[144:145], v[132:135], off
	s_waitcnt lgkmcnt(0)
	v_add_f32_e32 v131, v131, v147
	v_xor_b32_e32 v132, 32, v221
	v_cmp_lt_i32_e32 vcc, v132, v146
	v_cvt_pk_bf16_f32 v134, v138, v139
	v_cvt_pk_bf16_f32 v135, v140, v141
	v_cvt_pk_bf16_f32 v136, v136, v137
	v_cvt_pk_bf16_f32 v137, v142, v143
	global_store_dwordx4 v[144:145], v[134:137], off offset:256
	s_nop 0
	v_cndmask_b32_e32 v132, v221, v132, vcc
	v_lshlrev_b32_e32 v132, 2, v132
	v_mov_b32_e32 v132, v131
	s_nop 1
	v_permlane32_swap_b32_e32 v131, v132
	s_and_saveexec_b64 s[6:7], s[4:5]
	s_cbranch_execz .LBB0_1486
	v_lshl_add_u32 v130, v130, 4, s15
	s_waitcnt lgkmcnt(0)
	v_add_f32_e32 v131, v131, v132
	ds_write_b32 v130, v131
